# norm loop: 4 far-ahead dummy loads (rows +2,+3 strides) to raise bytes in flight; wait relaxed to vmcnt(4)
# speedup vs baseline: 1.0104x; 1.0044x over previous
.LBB0_545:
	v_pk_mul_f32 v[70:71], v[116:117], v[116:117]
	v_pk_mul_f32 v[72:73], v[112:113], v[112:113]
	v_pk_mul_f32 v[66:67], v[114:115], v[114:115]
	v_pk_mul_f32 v[68:69], v[110:111], v[110:111]
	v_pk_mov_b32 v[74:75], v[72:73], v[70:71] op_sel:[1,0]
	v_mov_b32_e32 v73, v71
	v_pk_add_f32 v[70:71], v[74:75], v[72:73]
	v_pk_mov_b32 v[72:73], v[68:69], v[66:67] op_sel:[1,0]
	v_mov_b32_e32 v69, v67
	v_pk_add_f32 v[66:67], v[72:73], v[68:69]
	v_pk_add_f32 v[70:71], v[70:71], v[70:71] op_sel_hi:[0,1]
	v_pk_add_f32 v[66:67], v[66:67], v[66:67] op_sel_hi:[0,1]
	v_mul_f32_e32 v66, v106, v106
	v_pk_fma_f32 v[68:69], v[106:107], v[106:107], v[66:67] op_sel_hi:[1,1,0]
	v_mul_f32_e32 v66, v108, v108
	v_pk_fma_f32 v[72:73], v[108:109], v[108:109], v[66:67] op_sel_hi:[1,1,0]
	v_mul_f32_e32 v68, v102, v102
	v_mul_f32_e32 v72, v103, v103
	v_mul_f32_e32 v70, v104, v104
	v_mul_f32_e32 v66, v105, v105
	v_pk_add_f32 v[68:69], v[68:69], v[72:73]
	v_pk_add_f32 v[66:67], v[70:71], v[66:67]
	v_cmp_lt_i32_e32 vcc, v221, v220
	v_pk_add_f32 v[66:67], v[68:69], v[66:67]
	s_waitcnt vmcnt(4)
	v_mov_b64_e32 v[80:81], v[64:65]
	v_add_f32_e32 v66, v66, v67
	v_cndmask_b32_e32 v67, v218, v221, vcc
	v_lshlrev_b32_e32 v67, 2, v67
	ds_bpermute_b32 v67, v67, v66
	v_cmp_lt_i32_e32 vcc, v222, v220
	v_mov_b64_e32 v[78:79], v[62:63]
	s_waitcnt lgkmcnt(0)
	v_add_f32_e32 v66, v66, v67
	v_cndmask_b32_e32 v67, v218, v222, vcc
	v_lshlrev_b32_e32 v67, 2, v67
	ds_bpermute_b32 v67, v67, v66
	v_cmp_lt_i32_e32 vcc, v223, v220
	s_waitcnt lgkmcnt(0)
	v_add_f32_e32 v66, v66, v67
	v_cndmask_b32_e32 v67, v218, v223, vcc
	v_lshlrev_b32_e32 v67, 2, v67
	ds_bpermute_b32 v67, v67, v66
	v_cmp_lt_i32_e32 vcc, v224, v220
	s_waitcnt lgkmcnt(0)
	v_add_f32_e32 v66, v66, v67
	v_cndmask_b32_e32 v67, v218, v224, vcc
	v_lshlrev_b32_e32 v67, 2, v67
	ds_bpermute_b32 v67, v67, v66
	v_cmp_lt_i32_e32 vcc, v225, v220
	s_waitcnt lgkmcnt(0)
	v_add_f32_e32 v66, v66, v67
	v_cndmask_b32_e32 v67, v218, v225, vcc
	v_lshlrev_b32_e32 v67, 2, v67
	ds_bpermute_b32 v67, v67, v66
	v_cmp_lt_i32_e32 vcc, v226, v220
	s_waitcnt lgkmcnt(0)
	v_add_f32_e32 v66, v66, v67
	v_cndmask_b32_e32 v67, v218, v226, vcc
	v_lshlrev_b32_e32 v67, 2, v67
	ds_bpermute_b32 v67, v67, v66
	s_waitcnt lgkmcnt(0)
	v_add_f32_e32 v66, v66, v67
	v_fmamk_f32 v66, v66, 0x3a800000, v209
	v_mul_f32_e32 v67, 0x4f800000, v66
	v_cmp_gt_f32_e32 vcc, s23, v66
	s_nop 1
	v_cndmask_b32_e32 v66, v66, v67, vcc
	v_sqrt_f32_e32 v67, v66
	s_nop 0
	v_add_u32_e32 v68, -1, v67
	v_fma_f32 v69, -v68, v67, v66
	v_cmp_ge_f32_e64 s[42:43], 0, v69
	v_add_u32_e32 v69, 1, v67
	s_nop 0
	v_cndmask_b32_e64 v68, v67, v68, s[42:43]
	v_fma_f32 v67, -v69, v67, v66
	v_cmp_lt_f32_e64 s[42:43], 0, v67
	s_nop 1
	v_cndmask_b32_e64 v67, v68, v69, s[42:43]
	v_mul_f32_e32 v68, 0x37800000, v67
	v_cndmask_b32_e32 v67, v67, v68, vcc
	v_cmp_class_f32_e32 vcc, v66, v210
	s_nop 1
	v_cndmask_b32_e32 v66, v67, v66, vcc
	v_div_scale_f32 v67, s[14:15], v66, v66, 1.0
	v_rcp_f32_e32 v68, v67
	v_readlane_b32 s14, v254, 49
	v_readlane_b32 s15, v254, 50
	v_fma_f32 v69, -v67, v68, 1.0
	v_fmac_f32_e32 v68, v69, v68
	v_div_scale_f32 v69, vcc, 1.0, v66, 1.0
	v_mul_f32_e32 v70, v69, v68
	v_fma_f32 v71, -v67, v70, v69
	v_fmac_f32_e32 v70, v71, v68
	v_fma_f32 v67, -v67, v70, v69
	v_div_fmas_f32 v67, v67, v68, v70
	v_div_fixup_f32 v70, v67, v66, 1.0
	v_pk_mul_f32 v[66:67], v[116:117], v[70:71] op_sel_hi:[1,0]
	v_pk_mul_f32 v[68:69], v[112:113], v[70:71] op_sel_hi:[1,0]
	v_pk_mul_f32 v[66:67], v[4:5], v[66:67]
	v_pk_mul_f32 v[68:69], v[2:3], v[68:69]
	v_pk_fma_f32 v[72:73], v[20:21], v[66:67], v[24:25]
	v_pk_fma_f32 v[66:67], v[18:19], v[68:69], v[22:23]
	v_pk_mul_f32 v[68:69], v[114:115], v[70:71] op_sel_hi:[1,0]
	v_pk_mul_f32 v[74:75], v[110:111], v[70:71] op_sel_hi:[1,0]
	v_pk_mul_f32 v[68:69], v[8:9], v[68:69]
	v_pk_mul_f32 v[74:75], v[6:7], v[74:75]
	v_pk_fma_f32 v[76:77], v[32:33], v[68:69], v[28:29]
	v_pk_fma_f32 v[68:69], v[30:31], v[74:75], v[26:27]
	v_cvt_pk_bf16_f32 v66, v66, v67
	v_cvt_pk_bf16_f32 v67, v72, v73
	v_lshl_add_u64 v[72:73], s[6:7], 0, v[96:97]
	v_cvt_pk_bf16_f32 v68, v68, v69
	v_cvt_pk_bf16_f32 v69, v76, v77
	global_store_dwordx4 v[72:73], v[66:69], off
	s_nop 1
	v_pk_mul_f32 v[66:67], v[108:109], v[70:71] op_sel_hi:[1,0]
	v_pk_mul_f32 v[68:69], v[106:107], v[70:71] op_sel_hi:[1,0]
	v_pk_mul_f32 v[66:67], v[12:13], v[66:67]
	v_pk_mul_f32 v[68:69], v[10:11], v[68:69]
	v_pk_fma_f32 v[72:73], v[44:45], v[66:67], v[36:37]
	v_pk_fma_f32 v[66:67], v[42:43], v[68:69], v[34:35]
	v_pk_mul_f32 v[68:69], v[104:105], v[70:71] op_sel_hi:[1,0]
	v_pk_mul_f32 v[70:71], v[102:103], v[70:71] op_sel_hi:[1,0]
	v_pk_mul_f32 v[68:69], v[16:17], v[68:69]
	v_pk_mul_f32 v[70:71], v[14:15], v[70:71]
	v_pk_fma_f32 v[74:75], v[48:49], v[68:69], v[40:41]
	v_pk_fma_f32 v[68:69], v[46:47], v[70:71], v[38:39]
	v_cvt_pk_bf16_f32 v66, v66, v67
	v_cvt_pk_bf16_f32 v67, v72, v73
	v_lshl_add_u64 v[70:71], s[6:7], 0, v[0:1]
	v_cvt_pk_bf16_f32 v68, v68, v69
	v_cvt_pk_bf16_f32 v69, v74, v75
	global_store_dwordx4 v[70:71], v[66:69], off
	s_add_u32 s6, s6, s14
	v_mov_b64_e32 v[76:77], v[56:57]
	v_mov_b64_e32 v[72:73], v[52:53]
	v_mov_b64_e32 v[68:69], v[60:61]
	s_addc_u32 s7, s7, s15
	s_andn2_b64 vcc, exec, s[12:13]
	v_mov_b64_e32 v[74:75], v[54:55]
	v_mov_b64_e32 v[70:71], v[50:51]
	v_mov_b64_e32 v[66:67], v[58:59]
	s_mov_b32 s14, s10
	s_cbranch_vccz .LBB0_561

.LBB0_554:
	s_add_i32 s18, s10, s60
	s_add_i32 s16, s18, s60
	s_min_i32 s18, s18, 0x43ff
	s_min_i32 s16, s16, 0x43ff
	s_mov_b32 s19, 0
	s_mov_b32 s17, 0
	v_lshl_add_u64 v[236:237], s[18:19], 11, v[92:93]
	v_lshl_add_u64 v[240:241], s[16:17], 11, v[92:93]
	global_load_dword v238, v[236:237], off
	global_load_dword v239, v[236:237], off offset:1024
	global_load_dword v242, v[240:241], off
	global_load_dword v243, v[240:241], off offset:1024
	s_cmpk_lt_i32 s14, 0x4000
	s_cselect_b64 s[16:17], -1, 0
	s_and_b64 s[18:19], s[2:3], s[16:17]
	s_mov_b64 s[16:17], -1
	s_and_b64 vcc, exec, s[18:19]
	s_cbranch_vccnz .LBB0_556
	v_lshlrev_b32_e32 v112, 16, v74
	v_and_b32_e32 v113, 0xffff0000, v74
	v_lshlrev_b32_e32 v116, 16, v75
	v_and_b32_e32 v117, 0xffff0000, v75
	v_lshlrev_b32_e32 v110, 16, v76
	v_and_b32_e32 v111, 0xffff0000, v76
	v_lshlrev_b32_e32 v114, 16, v77
	v_and_b32_e32 v115, 0xffff0000, v77
	v_lshlrev_b32_e32 v106, 16, v70
	v_and_b32_e32 v107, 0xffff0000, v70
	v_lshlrev_b32_e32 v108, 16, v71
	v_and_b32_e32 v109, 0xffff0000, v71
	v_lshlrev_b32_e32 v102, 16, v72
	v_and_b32_e32 v103, 0xffff0000, v72
	v_lshlrev_b32_e32 v104, 16, v73
	v_and_b32_e32 v105, 0xffff0000, v73
	s_mov_b64 s[16:17], 0
